# GLA scan chunk loads: incremental row addressing with per-unit stride registers
# baseline (speedup 1.0000x reference)
; __device__ __forceinline__ int TIDX() { int t = threadIdx.x; asm volatile("" : "+v"(t)); return t; }
; template <int TPW, int NCOL>
; __device__ __forceinline__ void gl_load(const P& p, int b, int ch, int vch, int lane, int dir, int g, int wv, GlRaw& R) {
;   int seq, T, c0; chunk_pos(g, seq, T, c0);
; #pragma unroll
;   for (int i = 0; i < TPW; ++i) {
;     int s = c0 + wv * TPW + i, t = dir ? T - 1 - s : s;
;     const u16* pr = p.projb + (unsigned)(tokrow(seq, b, t) * PROJP);
;     R.q[i] = pr[O_GQ + ch]; R.k[i] = pr[O_GK + ch]; R.v[i] = pr[O_GV + vch + (lane & (NCOL - 1))];
;     R.f[i] = p.glf[(unsigned)(((size_t)dir * NT + tokrow(seq, b, t)) * 256 + ch)];
;     R.kq[i] = p.kqa[(unsigned)(tokrow(seq, b, t) * 8 + 4 + (ch >> 6))];
;   }
; template <int NW>
; __device__ void scan_gla(const P& p, int l, int b, int h, int dir, int part, LAS char* lds) {
;     ...
;   const int tid = TIDX(), lane = tid & 63, wv = (tid >> 6) & (NW - 1), tl = tid & (NTH - 1);
;   const int ch = h * 64 + lane;
;   u16* oo = osc_ptr(p, 0, dir);
;   f32x2 S2[4];
; #pragma unroll
;   for (int i = 0; i < 4; ++i) S2[i] = (f32x2){0.f, 0.f};
;   const int col = tl >> 3, dq = tl & 7;
;   const int vch = h * 128 + part * NCOL;
.LBB0_134:
	s_ashr_i32 s64, s0, 3
	s_bitcmp1_b32 s0, 0
	s_cselect_b64 s[2:3], -1, 0
	v_writelane_b32 v238, s0, 54
	s_lshl_b32 s0, s0, 4
	s_and_b32 s65, s0, 0x60
	s_add_i32 s65, s65, s64
	s_mov_b64 s[0:1], -1
	s_and_b64 vcc, exec, s[2:3]
	s_cbranch_vccz .LBB0_283
	s_waitcnt vmcnt(0)
	v_mov_b32_e32 v0, v168
	v_readlane_b32 s1, v238, 54
	s_ashr_i32 s62, s65, 5
	v_readfirstlane_b32 s0, v0
	s_bfe_u32 s66, s1, 0x20006
	s_bfe_u32 s59, s64, 0x10002
	s_cmpk_gt_i32 s0, 0xff
	s_mov_b64 s[0:1], -1
	s_mul_i32 s28, s59, 0x4400
	s_mul_i32 s58, s59, 0x1100000
	s_cbranch_scc0 .LBB0_209
	s_lshl_b32 s1, s64, 5
	s_lshl_b32 s0, s66, 7
	s_and_b32 s1, s1, 0x60
	v_mov_b32_e32 v2, v168
	s_or_b32 s0, s1, s0
	s_cmp_eq_u32 s59, 0
	v_lshrrev_b32_e32 v0, 3, v2
	v_and_or_b32 v40, v2, 31, s0
	s_movk_i32 s0, 0xff
	v_and_b32_e32 v39, 24, v0
	s_cselect_b64 vcc, -1, 0
	v_mov_b32_e32 v252, 0xffffca00
	v_mov_b32_e32 v246, 0x3600
	v_cndmask_b32_e32 v246, v252, v246, vcc
	v_cndmask_b32_e64 v247, -1, 0, vcc
	v_mov_b32_e32 v252, 0xfffffc00
	v_mov_b32_e32 v248, 0x400
	v_cndmask_b32_e32 v248, v252, v248, vcc
	v_mov_b32_e32 v249, v247
	v_mov_b32_e32 v252, 0xffffffe0
	v_mov_b32_e32 v250, 32
	v_cndmask_b32_e32 v250, v252, v250, vcc
	v_mov_b32_e32 v251, v247
	s_lshl_b32 s23, s62, 8
	v_bitop3_b32 v0, v0, s0, 24 bitop3:0x6c
	s_addk_i32 s23, 0x4000
	v_cndmask_b32_e32 v0, v0, v39, vcc
	v_and_b32_e32 v37, 63, v2
	v_or_b32_e32 v3, s23, v0
	s_movk_i32 s20, 0x1b00
	v_lshl_or_b32 v38, s66, 6, v37
	v_mul_lo_u32 v128, v3, s20
	v_lshl_add_u64 v[0:1], v[128:129], 1, s[94:95]
	v_lshlrev_b32_e32 v24, 1, v38
	v_mov_b32_e32 v25, v129
	v_lshl_add_u64 v[4:5], v[0:1], 0, v[24:25]
	global_load_ushort v41, v[4:5], off
	global_load_ushort v50, v[4:5], off offset:512
	v_add_u32_e32 v4, s28, v3
	v_readlane_b32 s0, v239, 26
	v_lshl_or_b32 v128, v4, 8, v38
	v_readlane_b32 s1, v239, 27
	v_lshlrev_b32_e32 v26, 1, v40
	v_mov_b32_e32 v27, v129
	v_lshl_add_u64 v[4:5], v[128:129], 2, s[0:1]
	v_lshl_or_b32 v128, v3, 3, s66
	global_load_dword v51, v[4:5], off
	v_lshl_add_u64 v[4:5], v[128:129], 2, s[18:19]
	global_load_dword v3, v[4:5], off offset:16
	v_or_b32_e32 v4, 1, v39
	v_xad_u32 v5, v39, -2, v183
	v_cndmask_b32_e32 v4, v5, v4, vcc
	v_or_b32_e32 v10, s23, v4
	v_mul_lo_u32 v128, v10, s20
	v_lshl_add_u64 v[6:7], v[128:129], 1, s[94:95]
	v_lshl_add_u64 v[8:9], v[6:7], 0, v[24:25]
	v_lshl_add_u64 v[6:7], v[6:7], 0, v[26:27]
	global_load_ushort v5, v[8:9], off
	global_load_ushort v4, v[8:9], off offset:512
	v_cmp_gt_u32_e64 s[38:39], 32, v37
	global_load_ushort v6, v[6:7], off offset:1024
	v_add_u32_e32 v7, s28, v10
	v_lshl_or_b32 v128, v7, 8, v38
	v_lshl_add_u64 v[8:9], v[128:129], 2, s[0:1]
	v_lshl_or_b32 v128, v10, 3, s66
	global_load_dword v12, v[8:9], off
	v_lshl_add_u64 v[8:9], v[128:129], 2, s[18:19]
	global_load_dword v7, v[8:9], off offset:16
	v_or_b32_e32 v8, 2, v39
	v_xad_u32 v9, v39, -3, v183
	v_cndmask_b32_e32 v8, v9, v8, vcc
	v_or_b32_e32 v13, s23, v8
	v_mul_lo_u32 v128, v13, s20
	v_lshl_add_u64 v[10:11], v[128:129], 1, s[94:95]
	v_lshl_add_u64 v[14:15], v[10:11], 0, v[24:25]
	v_lshl_add_u64 v[10:11], v[10:11], 0, v[26:27]
	global_load_ushort v9, v[14:15], off
	global_load_ushort v8, v[14:15], off offset:512
	v_readlane_b32 s2, v239, 28
	global_load_ushort v10, v[10:11], off offset:1024
	v_add_u32_e32 v11, s28, v13
	v_lshl_or_b32 v128, v11, 8, v38
	v_lshl_add_u64 v[14:15], v[128:129], 2, s[0:1]
	v_lshl_or_b32 v128, v13, 3, s66
	global_load_dword v17, v[14:15], off
	v_lshl_add_u64 v[14:15], v[128:129], 2, s[18:19]
	global_load_dword v11, v[14:15], off offset:16
	v_or_b32_e32 v13, 3, v39
	v_xad_u32 v14, v39, -4, v183
	v_cndmask_b32_e32 v13, v14, v13, vcc
	v_or_b32_e32 v16, s23, v13
	v_mul_lo_u32 v128, v16, s20
	v_lshl_add_u64 v[18:19], v[128:129], 1, s[94:95]
	v_lshl_add_u64 v[20:21], v[18:19], 0, v[24:25]
	v_lshl_add_u64 v[18:19], v[18:19], 0, v[26:27]
	global_load_ushort v14, v[20:21], off
	global_load_ushort v13, v[20:21], off offset:512
	global_load_ushort v15, v[18:19], off offset:1024
	v_add_u32_e32 v18, s28, v16
	v_lshl_or_b32 v128, v18, 8, v38
	v_lshl_add_u64 v[18:19], v[128:129], 2, s[0:1]
	v_lshl_or_b32 v128, v16, 3, s66
	global_load_dword v22, v[18:19], off
	v_lshl_add_u64 v[18:19], v[128:129], 2, s[18:19]
	global_load_dword v16, v[18:19], off offset:16
	v_or_b32_e32 v18, 4, v39
	v_xad_u32 v19, v39, -5, v183
	v_cndmask_b32_e32 v18, v19, v18, vcc
	v_or_b32_e32 v23, s23, v18
	v_mul_lo_u32 v128, v23, s20
	v_lshl_add_u64 v[20:21], v[128:129], 1, s[94:95]
	v_lshl_add_u64 v[28:29], v[20:21], 0, v[24:25]
	v_lshl_add_u64 v[20:21], v[20:21], 0, v[26:27]
	global_load_ushort v19, v[28:29], off
	global_load_ushort v18, v[28:29], off offset:512
	v_readlane_b32 s3, v239, 29
	global_load_ushort v20, v[20:21], off offset:1024
	v_add_u32_e32 v21, s28, v23
	v_lshl_or_b32 v128, v21, 8, v38
	v_lshl_add_u64 v[28:29], v[128:129], 2, s[0:1]
	v_lshl_or_b32 v128, v23, 3, s66
	global_load_dword v31, v[28:29], off
	v_lshl_add_u64 v[28:29], v[128:129], 2, s[18:19]
	global_load_dword v21, v[28:29], off offset:16
	v_or_b32_e32 v23, 5, v39
	v_xad_u32 v28, v39, -6, v183
	v_cndmask_b32_e32 v23, v28, v23, vcc
	v_or_b32_e32 v30, s23, v23
	v_mul_lo_u32 v128, v30, s20
	v_lshl_add_u64 v[32:33], v[128:129], 1, s[94:95]
	v_lshl_add_u64 v[34:35], v[32:33], 0, v[24:25]
	v_lshl_add_u64 v[32:33], v[32:33], 0, v[26:27]
	global_load_ushort v28, v[34:35], off
	global_load_ushort v23, v[34:35], off offset:512
	global_load_ushort v29, v[32:33], off offset:1024
	v_add_u32_e32 v32, s28, v30
	v_lshl_or_b32 v128, v32, 8, v38
	v_lshl_add_u64 v[32:33], v[128:129], 2, s[0:1]
	v_lshl_or_b32 v128, v30, 3, s66
	global_load_dword v36, v[32:33], off
	v_lshl_add_u64 v[32:33], v[128:129], 2, s[18:19]
	global_load_dword v30, v[32:33], off offset:16
	v_or_b32_e32 v32, 6, v39
	v_xad_u32 v33, v39, -7, v183
	v_cndmask_b32_e32 v32, v33, v32, vcc
	v_or_b32_e32 v44, s23, v32
	v_mul_lo_u32 v128, v44, s20
	v_lshl_add_u64 v[34:35], v[128:129], 1, s[94:95]
	v_lshl_add_u64 v[42:43], v[34:35], 0, v[24:25]
	v_lshl_add_u64 v[34:35], v[34:35], 0, v[26:27]
	global_load_ushort v33, v[42:43], off
	global_load_ushort v32, v[42:43], off offset:512
	s_waitcnt vmcnt(0)
; template <int TPW, int NCOL>
; __device__ __forceinline__ void gl_load(const P& p, int b, int ch, int vch, int lane, int dir, int g, int wv, GlRaw& R) {
;     ...
;     int s = c0 + wv * TPW + i, t = dir ? T - 1 - s : s;
;     const u16* pr = p.projb + (unsigned)(tokrow(seq, b, t) * PROJP);
;     R.q[i] = pr[O_GQ + ch]; R.k[i] = pr[O_GK + ch]; R.v[i] = pr[O_GV + vch + (lane & (NCOL - 1))];
;     R.f[i] = p.glf[(unsigned)(((size_t)dir * NT + tokrow(seq, b, t)) * 256 + ch)];
;     R.kq[i] = p.kqa[(unsigned)(tokrow(seq, b, t) * 8 + 4 + (ch >> 6))];
;   }
	v_lshlrev_b32_e32 v41, 16, v41
	global_load_ushort v34, v[34:35], off offset:1024
	v_add_u32_e32 v35, s28, v44
	v_lshl_or_b32 v128, v35, 8, v38
	v_lshl_add_u64 v[42:43], v[128:129], 2, s[0:1]
	v_lshl_or_b32 v128, v44, 3, s66
	global_load_dword v45, v[42:43], off
	v_lshl_add_u64 v[42:43], v[128:129], 2, s[18:19]
	global_load_dword v35, v[42:43], off offset:16
	v_or_b32_e32 v42, 7, v39
	v_xad_u32 v43, v39, -8, v183
	v_cndmask_b32_e32 v42, v43, v42, vcc
	v_or_b32_e32 v44, s23, v42
	v_mul_lo_u32 v128, v44, s20
	v_lshl_add_u64 v[46:47], v[128:129], 1, s[94:95]
	v_lshl_add_u64 v[48:49], v[46:47], 0, v[24:25]
	v_lshl_add_u64 v[46:47], v[46:47], 0, v[26:27]
	global_load_ushort v42, v[48:49], off
	global_load_ushort v25, v[48:49], off offset:512
	global_load_ushort v43, v[46:47], off offset:1024
	v_add_u32_e32 v46, s28, v44
	v_lshl_or_b32 v128, v46, 8, v38
	v_lshl_add_u64 v[46:47], v[128:129], 2, s[0:1]
	v_lshl_or_b32 v128, v44, 3, s66
	v_lshl_add_u64 v[48:49], v[128:129], 2, s[18:19]
	global_load_dword v46, v[46:47], off
	v_readlane_b32 s20, v239, 32
	global_load_dword v44, v[48:49], off offset:16
	v_mul_f32_e32 v48, 0x3e000000, v41
	v_mov_b32_e32 v41, s20
	s_movk_i32 s0, 0x390
	v_mad_u32_u24 v41, v39, s0, v41
	v_lshlrev_b32_e32 v49, 16, v50
	v_lshl_add_u32 v47, v37, 2, v41
	v_mul_f32_e32 v48, v51, v48
	ds_write2st64_b32 v47, v51, v49 offset1:1
	ds_write_b32 v47, v48 offset:512
	s_and_saveexec_b64 s[0:1], s[38:39]
	s_cbranch_execz .LBB0_138
	v_lshl_add_u64 v[0:1], v[0:1], 0, v[26:27]
	global_load_ushort v0, v[0:1], off offset:1024
	s_waitcnt vmcnt(0)
	v_lshlrev_b32_e32 v0, 16, v0
	ds_write_b32 v47, v0 offset:768

; template <int TPW, int NCOL>
; __device__ __forceinline__ void gl_load(const P& p, int b, int ch, int vch, int lane, int dir, int g, int wv, GlRaw& R) {
;   int seq, T, c0; chunk_pos(g, seq, T, c0);
; #pragma unroll
;   for (int i = 0; i < TPW; ++i) {
;     int s = c0 + wv * TPW + i, t = dir ? T - 1 - s : s;
;     const u16* pr = p.projb + (unsigned)(tokrow(seq, b, t) * PROJP);
;     R.q[i] = pr[O_GQ + ch]; R.k[i] = pr[O_GK + ch]; R.v[i] = pr[O_GV + vch + (lane & (NCOL - 1))];
;     R.f[i] = p.glf[(unsigned)(((size_t)dir * NT + tokrow(seq, b, t)) * 256 + ch)];
;     R.kq[i] = p.kqa[(unsigned)(tokrow(seq, b, t) * 8 + 4 + (ch >> 6))];
;   }
; template <int NW>
; __device__ void scan_gla(const P& p, int l, int b, int h, int dir, int part, LAS char* lds) {
;     ...
;     if (g + 2 < NCHK) gl_load<TPW, NCOL>(p, b, ch, vch, lane, dir, g + 2, wv, R);
.LBB0_206:
	s_cmpk_gt_u32 s27, 0x85
	s_cbranch_scc1 .LBB0_169
	s_cmp_lt_u32 s27, 6
	s_cselect_b32 s20, 64, 0xffffff40
	s_cselect_b32 s22, 0x100, s96
	s_cselect_b32 s31, s23, s26
	s_add_i32 s20, s20, s33
	v_or_b32_e32 v4, s20, v39
	v_xad_u32 v0, v4, -1, s22
	v_cndmask_b32_e32 v0, v0, v4, vcc
	v_add_u32_e32 v5, s31, v0
	s_movk_i32 s20, 0x1b00
	v_mul_lo_u32 v128, v5, s20
	v_lshl_add_u64 v[0:1], v[128:129], 1, s[94:95]
	s_waitcnt vmcnt(4)
	v_mov_b32_e32 v25, v129
	s_waitcnt vmcnt(2)
	v_mov_b32_e32 v27, v129
	v_lshl_add_u64 v[2:3], v[0:1], 0, v[24:25]
	v_lshl_add_u64 v[252:253], v[0:1], 0, v[26:27]
	v_add_u32_e32 v0, s28, v5
	v_readlane_b32 s68, v239, 26
	v_lshl_or_b32 v128, v0, 8, v38
	v_readlane_b32 s69, v239, 27
	v_readlane_b32 s70, v239, 28
	v_readlane_b32 s71, v239, 29
	v_lshl_add_u64 v[254:255], v[128:129], 2, s[68:69]
	v_lshl_or_b32 v128, v5, 3, s66
	v_lshl_add_u64 v[244:245], v[128:129], 2, s[18:19]
	global_load_ushort v42, v[2:3], off
	global_load_ushort v43, v[2:3], off offset:512
	global_load_ushort v44, v[252:253], off offset:1024
	global_load_dword v45, v[254:255], off
	global_load_dword v46, v[244:245], off offset:16
	v_lshl_add_u64 v[2:3], v[2:3], 0, v[246:247]
	v_lshl_add_u64 v[252:253], v[252:253], 0, v[246:247]
	v_lshl_add_u64 v[254:255], v[254:255], 0, v[248:249]
	v_lshl_add_u64 v[244:245], v[244:245], 0, v[250:251]
	global_load_ushort v47, v[2:3], off
	global_load_ushort v48, v[2:3], off offset:512
	global_load_ushort v49, v[252:253], off offset:1024
	global_load_dword v50, v[254:255], off
	global_load_dword v51, v[244:245], off offset:16
	v_lshl_add_u64 v[2:3], v[2:3], 0, v[246:247]
	v_lshl_add_u64 v[252:253], v[252:253], 0, v[246:247]
	v_lshl_add_u64 v[254:255], v[254:255], 0, v[248:249]
	v_lshl_add_u64 v[244:245], v[244:245], 0, v[250:251]
	global_load_ushort v52, v[2:3], off
	global_load_ushort v53, v[2:3], off offset:512
	global_load_ushort v54, v[252:253], off offset:1024
	global_load_dword v55, v[254:255], off
	global_load_dword v56, v[244:245], off offset:16
	v_lshl_add_u64 v[2:3], v[2:3], 0, v[246:247]
	v_lshl_add_u64 v[252:253], v[252:253], 0, v[246:247]
	v_lshl_add_u64 v[254:255], v[254:255], 0, v[248:249]
	v_lshl_add_u64 v[244:245], v[244:245], 0, v[250:251]
	global_load_ushort v59, v[2:3], off
	global_load_ushort v61, v[2:3], off offset:512
	global_load_ushort v65, v[252:253], off offset:1024
	global_load_dword v68, v[254:255], off
	global_load_dword v69, v[244:245], off offset:16
	v_lshl_add_u64 v[2:3], v[2:3], 0, v[246:247]
	v_lshl_add_u64 v[252:253], v[252:253], 0, v[246:247]
	v_lshl_add_u64 v[254:255], v[254:255], 0, v[248:249]
	v_lshl_add_u64 v[244:245], v[244:245], 0, v[250:251]
	global_load_ushort v70, v[2:3], off
	global_load_ushort v71, v[2:3], off offset:512
	global_load_ushort v72, v[252:253], off offset:1024
	global_load_dword v73, v[254:255], off
	global_load_dword v74, v[244:245], off offset:16
	v_lshl_add_u64 v[2:3], v[2:3], 0, v[246:247]
	v_lshl_add_u64 v[252:253], v[252:253], 0, v[246:247]
	v_lshl_add_u64 v[254:255], v[254:255], 0, v[248:249]
	v_lshl_add_u64 v[244:245], v[244:245], 0, v[250:251]
	global_load_ushort v75, v[2:3], off
	global_load_ushort v76, v[2:3], off offset:512
	global_load_ushort v77, v[252:253], off offset:1024
	global_load_dword v78, v[254:255], off
	global_load_dword v79, v[244:245], off offset:16
	v_lshl_add_u64 v[2:3], v[2:3], 0, v[246:247]
	v_lshl_add_u64 v[252:253], v[252:253], 0, v[246:247]
	v_lshl_add_u64 v[254:255], v[254:255], 0, v[248:249]
	v_lshl_add_u64 v[244:245], v[244:245], 0, v[250:251]
	global_load_ushort v80, v[2:3], off
	global_load_ushort v81, v[2:3], off offset:512
	global_load_ushort v82, v[252:253], off offset:1024
	global_load_dword v83, v[254:255], off
	global_load_dword v84, v[244:245], off offset:16
	v_lshl_add_u64 v[2:3], v[2:3], 0, v[246:247]
	v_lshl_add_u64 v[252:253], v[252:253], 0, v[246:247]
	v_lshl_add_u64 v[254:255], v[254:255], 0, v[248:249]
	v_lshl_add_u64 v[244:245], v[244:245], 0, v[250:251]
	global_load_ushort v25, v[2:3], off
	global_load_ushort v85, v[2:3], off offset:512
	global_load_ushort v27, v[252:253], off offset:1024
	global_load_dword v86, v[254:255], off
	global_load_dword v87, v[244:245], off offset:16
	s_branch .LBB0_169
